# grid barrier rewritten flat: every workgroup writes back L2, one returning atomic on a single monotonic counter, polls that counter (no per-XCD election, no release word)
# baseline (speedup 1.0000x reference)
.LBB0_71:
	buffer_wbl2 sc1
	s_waitcnt lgkmcnt(0)
	v_mul_lo_u32 v2, v2, v0
	v_readlane_b32 s14, v253, 6
	v_readlane_b32 s15, v253, 7
	v_mov_b32_e32 v0, 0
	s_add_u32 s14, s14, 0x7400
	s_addc_u32 s15, s15, 0
	v_mov_b32_e32 v3, 1
	v_cvt_f32_u32_e32 v4, v2
	v_sub_u32_e32 v5, 0, v2
	v_rcp_iflag_f32_e32 v4, v4
	s_mov_b32 s3, 0
	s_waitcnt vmcnt(0) lgkmcnt(0)
	s_nop 4
	global_atomic_add v3, v0, v3, s[14:15] sc0
	v_mul_f32_e32 v4, 0x4f7ffffe, v4
	v_cvt_u32_f32_e32 v4, v4
	v_mul_lo_u32 v5, v5, v4
	v_mul_hi_u32 v5, v4, v5
	v_add_u32_e32 v4, v4, v5
	s_waitcnt vmcnt(0)
	v_mul_hi_u32 v1, v3, v4
	v_mul_lo_u32 v5, v1, v2
	v_sub_u32_e32 v5, v3, v5
	v_add_u32_e32 v4, 1, v1
	v_cmp_ge_u32_e32 vcc, v5, v2
	s_nop 1
	v_cndmask_b32_e32 v1, v1, v4, vcc
	v_sub_u32_e32 v4, v5, v2
	v_cndmask_b32_e32 v5, v5, v4, vcc
	v_add_u32_e32 v4, 1, v1
	v_cmp_ge_u32_e32 vcc, v5, v2
	s_nop 1
	v_cndmask_b32_e32 v1, v1, v4, vcc
	v_add_u32_e32 v1, 1, v1
	v_mul_lo_u32 v5, v1, v2
	v_add_u32_e32 v3, 1, v3
	v_cmp_ne_u32_e32 vcc, v3, v5
	s_cbranch_vccz .Lfb0_done
.Lfb0_spin:
	s_sleep 1
	global_load_dword v1, v0, s[14:15] sc1
	s_add_i32 s3, s3, 1
	s_cmp_lt_u32 s3, 0x40000
	s_cbranch_scc0 .Lfb0_done
	s_waitcnt vmcnt(0)
	v_cmp_lt_u32_e32 vcc, v1, v5
	s_cbranch_vccnz .Lfb0_spin
.Lfb0_done:
	s_waitcnt vmcnt(0)
	buffer_inv sc1
	s_waitcnt vmcnt(0)

.LBB0_472:
	buffer_wbl2 sc1
	s_waitcnt lgkmcnt(0)
	v_mul_lo_u32 v2, v2, v0
	v_readlane_b32 s12, v253, 6
	v_readlane_b32 s13, v253, 7
	v_mov_b32_e32 v0, 0
	s_add_u32 s12, s12, 0x7400
	s_addc_u32 s13, s13, 0
	v_mov_b32_e32 v3, 1
	v_cvt_f32_u32_e32 v4, v2
	v_sub_u32_e32 v5, 0, v2
	v_rcp_iflag_f32_e32 v4, v4
	s_mov_b32 s3, 0
	s_waitcnt vmcnt(0) lgkmcnt(0)
	s_nop 4
	global_atomic_add v3, v0, v3, s[12:13] sc0
	v_mul_f32_e32 v4, 0x4f7ffffe, v4
	v_cvt_u32_f32_e32 v4, v4
	v_mul_lo_u32 v5, v5, v4
	v_mul_hi_u32 v5, v4, v5
	v_add_u32_e32 v4, v4, v5
	s_waitcnt vmcnt(0)
	v_mul_hi_u32 v1, v3, v4
	v_mul_lo_u32 v5, v1, v2
	v_sub_u32_e32 v5, v3, v5
	v_add_u32_e32 v4, 1, v1
	v_cmp_ge_u32_e32 vcc, v5, v2
	s_nop 1
	v_cndmask_b32_e32 v1, v1, v4, vcc
	v_sub_u32_e32 v4, v5, v2
	v_cndmask_b32_e32 v5, v5, v4, vcc
	v_add_u32_e32 v4, 1, v1
	v_cmp_ge_u32_e32 vcc, v5, v2
	s_nop 1
	v_cndmask_b32_e32 v1, v1, v4, vcc
	v_add_u32_e32 v1, 1, v1
	v_mul_lo_u32 v5, v1, v2
	v_add_u32_e32 v3, 1, v3
	v_cmp_ne_u32_e32 vcc, v3, v5
	s_cbranch_vccz .Lfb3_done
.Lfb3_spin:
	s_sleep 1
	global_load_dword v1, v0, s[12:13] sc1
	s_add_i32 s3, s3, 1
	s_cmp_lt_u32 s3, 0x40000
	s_cbranch_scc0 .Lfb3_done
	s_waitcnt vmcnt(0)
	v_cmp_lt_u32_e32 vcc, v1, v5
	s_cbranch_vccnz .Lfb3_spin

.LBB0_510:
	v_readlane_b32 s8, v253, 4
	v_readlane_b32 s10, v253, 6
	v_readlane_b32 s11, v253, 7
	s_add_u32 s0, s10, 0x22b00000
	v_writelane_b32 v254, s0, 28
	s_addc_u32 s0, s11, 0
	s_add_u32 s97, s10, 0x100000
	s_addc_u32 s3, s11, 0
	s_add_u32 s33, s10, 0x10100000
	v_readlane_b32 s6, v253, 0
	s_addc_u32 s68, s11, 0
	s_lshr_b32 s1, s6, 8
	v_writelane_b32 v254, s0, 34
	s_lshl_b32 s0, s1, 6
	v_readlane_b32 s9, v253, 5
	v_readlane_b32 s7, v253, 44
	s_bfe_u32 s4, s6, 0x20006
	v_writelane_b32 v253, s0, 28
	s_lshl_b32 s0, s1, 13
	s_lshl_b32 s69, s7, 10
	v_writelane_b32 v254, s0, 62
	s_lshl_b32 s0, s4, 12
	s_cmpk_lt_i32 s2, 0x800
	s_cselect_b64 s[8:9], -1, 0
	s_ashr_i32 s73, s2, 31
	v_writelane_b32 v253, s0, 60
	s_lshr_b32 s0, s73, 29
	s_add_i32 s5, s2, s0
	s_ashr_i32 s0, s5, 3
	s_and_b32 s5, s5, -8
	v_writelane_b32 v253, s8, 62
	s_sub_i32 s5, s2, s5
	v_mov_b32_e32 v129, 0
	v_writelane_b32 v253, s9, 63
	s_lshl_b32 s8, s5, 8
	s_cmp_eq_u32 s1, 1
	s_cselect_b64 s[20:21], -1, 0
	s_cmpk_lt_u32 s6, 0x100
	s_cselect_b64 s[48:49], -1, 0
	s_lshl_b32 s1, s7, 6
	s_bfe_u32 s74, s7, 0x10001
	s_and_b32 s1, s1, 64
	s_add_u32 s6, s33, s1
	s_addc_u32 s7, s68, 0
	v_writelane_b32 v254, s6, 2
	s_ashr_i32 s75, s96, 31
	s_mov_b64 s[34:35], s[20:21]
	v_writelane_b32 v254, s7, 3
	s_add_u32 s6, s10, 0x4200
	s_addc_u32 s7, s11, 0
	v_writelane_b32 v254, s6, 26
	v_cndmask_b32_e64 v165, 0, 1, s[20:21]
	v_mov_b32_e32 v167, 1
	v_writelane_b32 v254, s7, 27
	s_add_u32 s6, s10, 0x4400
	s_addc_u32 s7, s11, 0
	v_writelane_b32 v254, s6, 32
	v_mov_b32_e32 v169, 0x358637bd
	v_mov_b64_e32 v[130:131], 0x800
	v_writelane_b32 v254, s7, 33
	s_add_u32 s6, s10, 0x4500
	s_addc_u32 s7, s11, 0
	v_writelane_b32 v254, s6, 36
	v_mov_b64_e32 v[132:133], 0x7ff
	v_mov_b64_e32 v[134:135], 0x200
	v_writelane_b32 v254, s7, 37
	s_add_u32 s6, s10, 0x4600
	s_addc_u32 s7, s11, 0
	v_writelane_b32 v254, s6, 38
	v_mov_b64_e32 v[136:137], 0x1ff
	s_mov_b32 s23, 0x10000
	v_writelane_b32 v254, s7, 39
	s_add_u32 s6, s10, 0x4700
	s_addc_u32 s7, s11, 0
	v_writelane_b32 v254, s6, 40
	s_movk_i32 s82, 0x4000
	s_movk_i32 s84, 0x1000
	v_writelane_b32 v254, s7, 41
	s_add_u32 s6, s10, 0x4800
	s_addc_u32 s7, s11, 0
	v_writelane_b32 v254, s6, 42
	s_mov_b32 s85, 0x11000
	s_movk_i32 s50, 0x5000
	v_writelane_b32 v254, s7, 43
	s_add_u32 s6, s10, 0x4900
	s_addc_u32 s7, s11, 0
	v_writelane_b32 v254, s6, 44
	s_mov_b32 s51, 0x15000
	s_mov_b32 s78, 0
	v_writelane_b32 v254, s7, 45
	s_add_u32 s6, s10, 0x4a00
	s_addc_u32 s7, s11, 0
	v_writelane_b32 v254, s6, 46
	s_nop 1
	v_writelane_b32 v254, s7, 47
	s_add_u32 s6, s10, 0x4b00
	s_addc_u32 s7, s11, 0
	v_writelane_b32 v254, s6, 48
	s_nop 1
	v_writelane_b32 v254, s7, 49
	s_add_u32 s6, s10, 0x4c00
	s_addc_u32 s7, s11, 0
	v_writelane_b32 v254, s6, 50
	s_nop 1
	v_writelane_b32 v254, s7, 51
	s_add_u32 s6, s10, 0x4d00
	s_addc_u32 s7, s11, 0
	v_writelane_b32 v254, s6, 52
	s_nop 1
	v_writelane_b32 v254, s7, 53
	s_add_u32 s6, s10, 0x4e00
	s_addc_u32 s7, s11, 0
	v_writelane_b32 v254, s6, 54
	s_nop 1
	v_writelane_b32 v254, s7, 55
	s_add_u32 s6, s10, 0x4f00
	s_addc_u32 s7, s11, 0
	v_writelane_b32 v254, s6, 20
	s_nop 1
	v_writelane_b32 v254, s7, 21
	s_add_u32 s6, s10, 0x5000
	s_addc_u32 s7, s11, 0
	v_writelane_b32 v254, s6, 22
	s_nop 1
	v_writelane_b32 v254, s7, 23
	s_add_u32 s6, s10, 0x5100
	s_addc_u32 s7, s11, 0
	v_writelane_b32 v254, s6, 58
	s_nop 1
	v_writelane_b32 v254, s7, 59
	s_add_u32 s6, s10, 0x5200
	s_addc_u32 s7, s11, 0
	v_writelane_b32 v253, s6, 58
	s_nop 1
	v_writelane_b32 v253, s7, 59
	s_add_u32 s6, s10, 0x5300
	s_addc_u32 s7, s11, 0
	v_readlane_b32 s1, v253, 26
	v_writelane_b32 v254, s6, 24
	s_cmp_eq_u32 s1, 15
	s_nop 0
	v_writelane_b32 v254, s7, 25
	s_cselect_b64 s[6:7], -1, 0
	v_writelane_b32 v255, s6, 0
	s_cmp_eq_u32 s1, 14
	s_nop 0
	v_writelane_b32 v255, s7, 1
	s_cselect_b64 s[6:7], -1, 0
	v_writelane_b32 v255, s6, 2
	s_cmp_eq_u32 s1, 13
	s_nop 0
	v_writelane_b32 v255, s7, 3
	s_cselect_b64 s[6:7], -1, 0
	v_writelane_b32 v255, s6, 4
	s_cmp_eq_u32 s1, 12
	s_nop 0
	v_writelane_b32 v255, s7, 5
	s_cselect_b64 s[6:7], -1, 0
	v_writelane_b32 v255, s6, 6
	s_cmp_eq_u32 s1, 11
	s_nop 0
	v_writelane_b32 v255, s7, 7
	s_cselect_b64 s[6:7], -1, 0
	v_writelane_b32 v255, s6, 8
	s_cmp_eq_u32 s1, 10
	s_nop 0
	v_writelane_b32 v255, s7, 9
	s_cselect_b64 s[6:7], -1, 0
	v_writelane_b32 v255, s6, 10
	s_cmp_eq_u32 s1, 9
	s_nop 0
	v_writelane_b32 v255, s7, 11
	s_cselect_b64 s[6:7], -1, 0
	v_writelane_b32 v255, s6, 12
	s_cmp_eq_u32 s1, 8
	s_nop 0
	v_writelane_b32 v255, s7, 13
	s_cselect_b64 s[6:7], -1, 0
	v_writelane_b32 v255, s6, 14
	s_cmp_eq_u32 s1, 7
	s_nop 0
	v_writelane_b32 v255, s7, 15
	s_cselect_b64 s[6:7], -1, 0
	v_writelane_b32 v255, s6, 16
	s_cmp_eq_u32 s1, 6
	s_nop 0
	v_writelane_b32 v255, s7, 17
	s_cselect_b64 s[6:7], -1, 0
	v_writelane_b32 v255, s6, 18
	s_cmp_eq_u32 s1, 5
	s_nop 0
	v_writelane_b32 v255, s7, 19
	s_cselect_b64 s[6:7], -1, 0
	v_writelane_b32 v255, s6, 20
	s_cmp_eq_u32 s1, 4
	s_nop 0
	v_writelane_b32 v255, s7, 21
	s_cselect_b64 s[6:7], -1, 0
	v_writelane_b32 v255, s6, 22
	s_cmp_eq_u32 s1, 3
	s_nop 0
	v_writelane_b32 v255, s7, 23
	s_cselect_b64 s[6:7], -1, 0
	v_writelane_b32 v255, s6, 24
	s_cmp_eq_u32 s1, 2
	s_nop 0
	v_writelane_b32 v255, s7, 25
	s_cselect_b64 s[6:7], -1, 0
	v_writelane_b32 v255, s6, 26
	s_cmp_eq_u32 s1, 1
	s_nop 0
	v_writelane_b32 v255, s7, 27
	s_cselect_b64 s[6:7], -1, 0
	v_writelane_b32 v255, s6, 28
	s_cmp_eq_u32 s1, 0
	s_nop 0
	v_writelane_b32 v255, s7, 29
	s_cselect_b64 s[6:7], -1, 0
	v_writelane_b32 v255, s6, 30
	s_lshl_b32 s1, s1, 8
	s_nop 0
	v_writelane_b32 v255, s7, 31
	v_readlane_b32 s6, v253, 24
	v_readlane_b32 s7, v253, 25
	s_add_u32 s1, s6, s1
	s_addc_u32 s6, s7, 0
	s_add_u32 s12, s1, 0x1400
	s_addc_u32 s13, s6, 0
	v_writelane_b32 v255, s12, 32
	s_nop 1
	v_writelane_b32 v255, s13, 33
	s_add_u32 s12, s1, 0x2400
	s_addc_u32 s13, s6, 0
	s_add_u32 s6, s10, 0x7400
	s_addc_u32 s7, s11, 0
	v_writelane_b32 v255, s6, 34
	v_writelane_b32 v254, s12, 60
	s_nop 0
	v_writelane_b32 v255, s7, 35
	s_add_u32 s6, s10, 0x7500
	s_addc_u32 s7, s11, 0
	s_add_u32 s76, s10, 0x8100000
	s_addc_u32 s77, s11, 0
	v_writelane_b32 v253, s6, 26
	s_cmpk_lg_i32 s96, 0x100
	v_writelane_b32 v254, s13, 61
	v_writelane_b32 v253, s7, 27
	s_cselect_b64 s[6:7], -1, 0
	s_add_u32 s1, s10, 0x40000
	v_writelane_b32 v253, s1, 48
	s_addc_u32 s1, s11, 0
	v_readlane_b32 s12, v253, 50
	v_readlane_b32 s19, v253, 57
	v_writelane_b32 v255, s1, 36
	s_lshl_b32 s9, s4, 5
	s_add_i32 s1, s19, -1
	s_cmpk_lt_i32 s2, 0x200
	v_readlane_b32 s13, v253, 51
	v_readlane_b32 s14, v253, 52
	v_readlane_b32 s15, v253, 53
	v_readlane_b32 s16, v253, 54
	v_readlane_b32 s17, v253, 55
	v_readlane_b32 s18, v253, 56
	v_writelane_b32 v253, s1, 24
	s_cselect_b64 s[10:11], -1, 0
	s_lshl_b32 s1, s2, 1
	s_and_b32 s1, s1, 8
	s_bfe_u32 s4, s2, 0x30003
	s_or_b32 s79, s1, s4
	s_lshl_b32 s1, s2, 2
	v_writelane_b32 v254, s10, 0
	s_and_b32 s80, s1, 12
	s_ashr_i32 s1, s2, 6
	v_writelane_b32 v254, s11, 1
	s_add_i32 s80, s80, s1
	s_lshl_b32 s1, s5, 6
	s_and_b32 s10, s9, 32
	s_cmp_lt_i32 s5, 0
	s_mul_i32 s4, s5, 0x101
	s_cselect_b32 s4, s4, s8
	s_mulk_i32 s5, 0x41
	s_cselect_b32 s1, s5, s1
	s_add_i32 s4, s4, s0
	s_ashr_i32 s5, s4, 31
	s_lshr_b32 s5, s5, 23
	s_add_i32 s5, s4, s5
	s_and_b32 s8, s5, 0xfe00
	s_sub_i32 s4, s4, s8
	s_sext_i32_i16 s8, s4
	s_bfe_u32 s8, s8, 0x3001c
	s_add_i32 s8, s4, s8
	v_writelane_b32 v254, s9, 4
	s_and_b32 s9, s8, 0xfff8
	s_sub_i32 s4, s4, s9
	s_ashr_i32 s5, s5, 9
	s_lshl_b32 s5, s5, 3
	s_sext_i32_i16 s8, s8
	s_sext_i32_i16 s4, s4
	s_add_i32 s12, s5, s4
	s_ashr_i32 s4, s8, 3
	v_writelane_b32 v254, s4, 8
	s_lshr_b32 s4, s8, 3
	s_mov_b32 s8, s12
	s_ashr_i32 s13, s12, 31
	s_bfe_i64 s[4:5], s[4:5], 0x100000
	v_writelane_b32 v254, s8, 6
	s_lshl_b64 s[4:5], s[4:5], 21
	s_nop 0
	v_writelane_b32 v254, s9, 7
	s_lshl_b64 s[8:9], s[12:13], 21
	s_add_u32 s12, s97, s4
	s_addc_u32 s13, s3, s5
	s_add_u32 s4, s12, 0x4000
	s_addc_u32 s5, s13, 0
	v_writelane_b32 v254, s4, 10
	v_writelane_b32 v255, s8, 37
	s_nop 0
	v_writelane_b32 v254, s5, 11
	s_add_u32 s4, s12, 0x8000
	s_addc_u32 s5, s13, 0
	v_writelane_b32 v254, s4, 12
	v_writelane_b32 v255, s9, 38
	s_nop 0
	v_writelane_b32 v254, s5, 13
	s_add_u32 s4, s12, 0xc000
	s_addc_u32 s5, s13, 0
	s_add_i32 s0, s1, s0
	s_ashr_i32 s1, s0, 31
	s_lshr_b32 s1, s1, 25
	v_writelane_b32 v254, s4, 14
	s_add_i32 s1, s0, s1
	s_nop 0
	v_writelane_b32 v254, s5, 15
	s_and_b32 s4, s1, 0xff80
	s_sub_i32 s0, s0, s4
	s_bfe_i32 s4, s0, 0x80000
	s_bfe_u32 s4, s4, 0x3000c
	s_add_i32 s4, s0, s4
	s_and_b32 s5, s4, 0xf8
	s_sub_i32 s0, s0, s5
	s_ashr_i32 s1, s1, 7
	s_lshl_b32 s1, s1, 3
	s_sext_i32_i8 s0, s0
	s_add_i32 s1, s1, s0
	s_bfe_i32 s0, s4, 0x80000
	s_sext_i32_i16 s0, s0
	s_ashr_i32 s0, s0, 3
	s_cmpk_eq_i32 s96, 0x100
	s_cselect_b32 s14, s80, s0
	s_cselect_b32 s8, s79, s1
	s_lshl_b32 s0, s14, 2
	s_or_b32 s0, s0, s74
	s_lshl_b32 s1, s8, 6
	s_add_i32 s0, s0, s1
	s_ashr_i32 s1, s0, 31
	s_lshl_b64 s[0:1], s[0:1], 15
	v_writelane_b32 v255, s0, 39
	s_ashr_i32 s9, s8, 31
	s_lshl_b32 s4, s8, 8
	v_writelane_b32 v255, s1, 40
	s_mov_b32 s0, s8
	v_writelane_b32 v254, s0, 18
	s_ashr_i32 s15, s14, 31
	s_ashr_i32 s5, s4, 31
	v_writelane_b32 v254, s1, 19
	s_lshl_b64 s[0:1], s[8:9], 23
	s_mov_b32 s8, s14
	v_writelane_b32 v254, s8, 16
	s_nop 1
	v_writelane_b32 v254, s9, 17
	s_lshl_b64 s[8:9], s[14:15], 23
	s_add_u32 s26, s76, s8
	s_addc_u32 s27, s77, s9
	s_add_u32 s8, s26, 0x4000
	s_addc_u32 s9, s27, 0
	s_add_u32 s30, s33, s0
	s_addc_u32 s31, s68, s1
	s_add_u32 s0, s30, 0x4000
	s_addc_u32 s1, s31, 0
	s_add_u32 s42, s26, 0x8000
	s_addc_u32 s43, s27, 0
	s_add_u32 s86, s30, 0x8000
	v_writelane_b32 v254, s0, 29
	s_addc_u32 s87, s31, 0
	v_writelane_b32 v253, s8, 8
	v_writelane_b32 v254, s1, 30
	s_add_u32 s0, s26, 0xc000
	v_writelane_b32 v253, s9, 9
	s_addc_u32 s1, s27, 0
	s_lshl_b32 s8, s10, 1
	v_writelane_b32 v255, s8, 41
	s_lshl_b64 s[4:5], s[4:5], 2
	v_writelane_b32 v255, s4, 42
	s_mov_b32 s9, 0x14000
	s_nop 0
	v_writelane_b32 v255, s5, 43
	s_add_i32 s4, 0, 0x20160
	v_writelane_b32 v255, s4, 44
	s_add_i32 s4, 0, 0x20164
	s_mov_b32 s5, 0
	v_writelane_b32 v255, s4, 45
	v_writelane_b32 v254, s4, 56
	s_nop 1
	v_writelane_b32 v254, s5, 57
	s_branch .LBB0_515
.LBB0_512:
	s_or_b64 exec, exec, s[4:5]

.LBB0_559:
	buffer_wbl2 sc1
	s_waitcnt lgkmcnt(0)
	v_mul_lo_u32 v2, v2, v0
	v_readlane_b32 s14, v255, 34
	v_readlane_b32 s15, v255, 35
	v_mov_b32_e32 v0, 0
	v_mov_b32_e32 v3, 1
	v_cvt_f32_u32_e32 v4, v2
	v_sub_u32_e32 v5, 0, v2
	v_rcp_iflag_f32_e32 v4, v4
	s_mov_b32 s10, 0
	s_waitcnt vmcnt(0) lgkmcnt(0)
	s_nop 4
	global_atomic_add v3, v0, v3, s[14:15] sc0
	v_mul_f32_e32 v4, 0x4f7ffffe, v4
	v_cvt_u32_f32_e32 v4, v4
	v_mul_lo_u32 v5, v5, v4
	v_mul_hi_u32 v5, v4, v5
	v_add_u32_e32 v4, v4, v5
	s_waitcnt vmcnt(0)
	v_mul_hi_u32 v1, v3, v4
	v_mul_lo_u32 v5, v1, v2
	v_sub_u32_e32 v5, v3, v5
	v_add_u32_e32 v4, 1, v1
	v_cmp_ge_u32_e32 vcc, v5, v2
	s_nop 1
	v_cndmask_b32_e32 v1, v1, v4, vcc
	v_sub_u32_e32 v4, v5, v2
	v_cndmask_b32_e32 v5, v5, v4, vcc
	v_add_u32_e32 v4, 1, v1
	v_cmp_ge_u32_e32 vcc, v5, v2
	s_nop 1
	v_cndmask_b32_e32 v1, v1, v4, vcc
	v_add_u32_e32 v1, 1, v1
	v_mul_lo_u32 v5, v1, v2
	v_add_u32_e32 v3, 1, v3
	v_cmp_ne_u32_e32 vcc, v3, v5
	s_cbranch_vccz .Lfb4_done
.Lfb4_spin:
	s_sleep 1
	global_load_dword v1, v0, s[14:15] sc1
	s_add_i32 s10, s10, 1
	s_cmp_lt_u32 s10, 0x40000
	s_cbranch_scc0 .Lfb4_done
	s_waitcnt vmcnt(0)
	v_cmp_lt_u32_e32 vcc, v1, v5
	s_cbranch_vccnz .Lfb4_spin

.Lfb5_done:
	s_waitcnt vmcnt(0)
	buffer_inv sc1
	s_waitcnt vmcnt(0)
	s_branch .LBB0_512
